# unit-order division by group size: shift/mask fast path when gsz==8 in P2/P5/P12 (generic float-reciprocal path kept for other values)
# speedup vs baseline: 1.0099x; 1.0099x over previous
.LBB0_564:
	s_add_i32 s57, s57, 1
	s_mul_i32 s2, s57, s70
	s_mul_hi_u32 s3, s57, s71
	s_add_i32 s3, s3, s2
	s_mul_i32 s2, s57, s71
	s_add_u32 s10, s2, s86
	s_addc_u32 s11, s3, s50
	v_cmp_gt_i64_e64 s[2:3], s[10:11], v[146:147]
	s_and_b64 vcc, exec, s[2:3]
	s_cbranch_vccnz .LBB0_566
	s_ashr_i32 s6, s10, 31
	s_lshr_b32 s6, s6, 29
	s_add_i32 s6, s10, s6
	s_ashr_i32 s7, s6, 3
	s_and_b32 s6, s6, -8
	s_sub_i32 s6, s10, s6
	s_cmp_lt_i32 s6, 0
	s_cselect_b32 s8, s51, 0x18c
	s_mul_i32 s6, s8, s6
	s_add_i32 s6, s6, s7
	s_mul_hi_i32 s7, s6, 0x2e8ba2e9
	s_lshr_b32 s8, s7, 31
	s_ashr_i32 s7, s7, 5
	s_add_i32 s7, s7, s8
	s_lshl_b32 s8, s7, 3
	s_sub_i32 s9, 0x90, s8
	s_min_i32 s9, s9, 8
	s_cmp_lg_u32 s9, 8
	s_cbranch_scc1 .Lp2_slowdiv
	s_mulk_i32 s7, 0xb0
	s_sub_i32 s7, s6, s7
	s_lshr_b32 s6, s7, 3
	s_and_b32 s7, s7, 7
	s_add_i32 s8, s7, s8
	s_branch .LBB0_566
.Lp2_slowdiv:
	s_abs_i32 s12, s9
	v_cvt_f32_u32_e32 v2, s12
	s_sub_i32 s18, 0, s12
	s_mulk_i32 s7, 0xb0
	s_sub_i32 s7, s6, s7
	v_rcp_iflag_f32_e32 v2, v2
	s_abs_i32 s6, s7
	s_xor_b32 s13, s7, s9
	s_ashr_i32 s13, s13, 31
	v_mul_f32_e32 v2, 0x4f7ffffe, v2
	v_cvt_u32_f32_e32 v2, v2
	s_nop 0
	v_readfirstlane_b32 s19, v2
	s_mul_i32 s18, s18, s19
	s_mul_hi_u32 s18, s19, s18
	s_add_i32 s19, s19, s18
	s_mul_hi_u32 s18, s6, s19
	s_mul_i32 s19, s18, s12
	s_sub_i32 s6, s6, s19
	s_add_i32 s20, s18, 1
	s_sub_i32 s19, s6, s12
	s_cmp_ge_u32 s6, s12
	s_cselect_b32 s18, s20, s18
	s_cselect_b32 s6, s19, s6
	s_add_i32 s19, s18, 1
	s_cmp_ge_u32 s6, s12
	s_cselect_b32 s6, s19, s18
	s_xor_b32 s6, s6, s13
	s_sub_i32 s6, s6, s13
	s_mul_i32 s9, s6, s9
	s_sub_i32 s7, s7, s9
	s_add_i32 s8, s7, s8

.LBB0_1372:
	s_andn2_b64 vcc, exec, s[50:51]
	s_cbranch_vccnz .LBB0_1374
	s_ashr_i32 s3, s48, 31
	s_lshr_b32 s3, s3, 29
	s_add_i32 s3, s48, s3
	s_ashr_i32 s5, s3, 3
	s_and_b32 s3, s3, -8
	s_sub_i32 s3, s48, s3
	s_cmp_lt_i32 s3, 0
	s_cselect_b32 s18, s70, 0x180
	s_mul_i32 s3, s18, s3
	s_add_i32 s3, s3, s5
	s_mul_hi_i32 s5, s3, 0x2aaaaaab
	s_lshr_b32 s18, s5, 31
	s_ashr_i32 s5, s5, 5
	s_add_i32 s5, s5, s18
	s_lshl_b32 s18, s5, 3
	s_sub_i32 s19, 0x80, s18
	s_min_i32 s19, s19, 8
	s_cmp_lg_u32 s19, 8
	s_cbranch_scc1 .Lp5_slowdiv
	s_mulk_i32 s5, 0xc0
	s_sub_i32 s3, s3, s5
	s_lshr_b32 s38, s3, 3
	s_and_b32 s3, s3, 7
	s_add_i32 s40, s3, s18
	s_mov_b64 s[18:19], -1
	s_branch .LBB0_1374
.Lp5_slowdiv:
	s_abs_i32 s20, s19
	v_cvt_f32_u32_e32 v2, s20
	s_sub_i32 s38, 0, s20
	s_mulk_i32 s5, 0xc0
	s_sub_i32 s3, s3, s5
	v_rcp_iflag_f32_e32 v2, v2
	s_abs_i32 s5, s3
	s_xor_b32 s21, s3, s19
	s_ashr_i32 s21, s21, 31
	v_mul_f32_e32 v2, 0x4f7ffffe, v2
	v_cvt_u32_f32_e32 v2, v2
	s_nop 0
	v_readfirstlane_b32 s39, v2
	s_mul_i32 s38, s38, s39
	s_mul_hi_u32 s38, s39, s38
	s_add_i32 s39, s39, s38
	s_mul_hi_u32 s38, s5, s39
	s_mul_i32 s39, s38, s20
	s_sub_i32 s5, s5, s39
	s_add_i32 s40, s38, 1
	s_sub_i32 s39, s5, s20
	s_cmp_ge_u32 s5, s20
	s_cselect_b32 s38, s40, s38
	s_cselect_b32 s5, s39, s5
	s_add_i32 s39, s38, 1
	s_cmp_ge_u32 s5, s20
	s_cselect_b32 s5, s39, s38
	s_xor_b32 s5, s5, s21
	s_sub_i32 s38, s5, s21
	s_mul_i32 s5, s38, s19
	s_sub_i32 s3, s3, s5
	s_add_i32 s40, s3, s18
	s_mov_b64 s[18:19], -1

.LBB0_3262:
	s_add_i32 s47, s47, 1
	s_mul_i32 s2, s47, s52
	s_mul_hi_u32 s3, s47, s53
	s_add_i32 s3, s3, s2
	s_mul_i32 s2, s47, s53
	s_add_u32 s12, s2, s86
	s_addc_u32 s13, s3, s40
	v_cmp_gt_i64_e64 s[2:3], s[12:13], v[164:165]
	s_and_b64 vcc, exec, s[2:3]
	s_cbranch_vccnz .LBB0_3264
	s_ashr_i32 s8, s12, 31
	s_lshr_b32 s8, s8, 29
	s_add_i32 s8, s12, s8
	s_ashr_i32 s9, s8, 3
	s_and_b32 s8, s8, -8
	s_sub_i32 s8, s12, s8
	s_cmp_lt_i32 s8, 0
	s_cselect_b32 s10, s41, 0x160
	s_mul_i32 s8, s10, s8
	s_add_i32 s8, s8, s9
	s_mul_hi_i32 s9, s8, 0x2e8ba2e9
	s_lshr_b32 s10, s9, 31
	s_ashr_i32 s9, s9, 5
	s_add_i32 s9, s9, s10
	s_lshl_b32 s10, s9, 3
	s_sub_i32 s11, 0x80, s10
	s_min_i32 s11, s11, 8
	s_cmp_lg_u32 s11, 8
	s_cbranch_scc1 .Lp12_slowdiv
	s_mulk_i32 s9, 0xb0
	s_sub_i32 s9, s8, s9
	s_lshr_b32 s8, s9, 3
	s_and_b32 s9, s9, 7
	s_add_i32 s10, s9, s10
	s_branch .LBB0_3264
.Lp12_slowdiv:
	s_abs_i32 s14, s11
	v_cvt_f32_u32_e32 v2, s14
	s_sub_i32 s18, 0, s14
	s_mulk_i32 s9, 0xb0
	s_sub_i32 s9, s8, s9
	v_rcp_iflag_f32_e32 v2, v2
	s_abs_i32 s8, s9
	s_xor_b32 s15, s9, s11
	s_ashr_i32 s15, s15, 31
	v_mul_f32_e32 v2, 0x4f7ffffe, v2
	v_cvt_u32_f32_e32 v2, v2
	s_nop 0
	v_readfirstlane_b32 s19, v2
	s_mul_i32 s18, s18, s19
	s_mul_hi_u32 s18, s19, s18
	s_add_i32 s19, s19, s18
	s_mul_hi_u32 s18, s8, s19
	s_mul_i32 s19, s18, s14
	s_sub_i32 s8, s8, s19
	s_add_i32 s20, s18, 1
	s_sub_i32 s19, s8, s14
	s_cmp_ge_u32 s8, s14
	s_cselect_b32 s18, s20, s18
	s_cselect_b32 s8, s19, s8
	s_add_i32 s19, s18, 1
	s_cmp_ge_u32 s8, s14
	s_cselect_b32 s8, s19, s18
	s_xor_b32 s8, s8, s15
	s_sub_i32 s8, s8, s15
	s_mul_i32 s11, s8, s11
	s_sub_i32 s9, s9, s11
	s_add_i32 s10, s9, s10
